# gate/up phase: the two wave halves run the SwiGLU epilogue together (leading half waits one barrier before it, trailing half one after), on the 12472 split
# speedup vs baseline: 1.0048x; 1.0048x over previous
; __host__ __device__ __forceinline__ size_t blk_off(int row, int col, int K) { return (size_t)((row >> 8) * (K >> 6) + (col >> 6)) * 16384 + ((row >> 7) & 1) * 8192 + (lds_byte(row & 127, col & 63) >> 1); }
; __device__ __forceinline__ unsigned cvt_pk_bf16(float lo, float hi) { unsigned r; asm volatile("v_cvt_pk_bf16_f32 %0, %1, %2" : "=v"(r) : "v"(lo), "v"(hi)); return r; }
;     __device__ __forceinline__ void operator()(const f32x4 (&acc)[2][2][4][2], const Unit& u, int wr, int wc, int fr, int fq) const {
;     ...
;         for (int ai = 0; ai < 2; ++ai)
; #pragma unroll
;             for (int m = 0; m < 4; ++m) { const int row = row0 + ai * HALF + m * 16; const float rs = rsv[ai][m];
;                 const float nl = -1.4426950408889634f * rs, ir = __builtin_amdgcn_rcpf(rs * rs);
;                 const f32x2 nl2 = {nl, nl}, ir2 = {ir, ir};
;                 float f[8];
; #pragma unroll
;                 for (int n = 0; n < 2; ++n)
; #pragma unroll
;                     for (int hh = 0; hh < 2; ++hh) { const f32x2 g2 = {acc[ai][0][m][n][2 * hh], acc[ai][0][m][n][2 * hh + 1]}, u2 = {acc[ai][1][m][n][2 * hh], acc[ai][1][m][n][2 * hh + 1]};
;                         const f32x2 t2 = g2 * nl2; const f32x2 e2 = {__builtin_amdgcn_exp2f(t2[0]), __builtin_amdgcn_exp2f(t2[1])};
;                         const f32x2 d2 = __builtin_elementwise_fma(e2, ir2, ir2); const f32x2 r2 = {__builtin_amdgcn_rcpf(d2[0]), __builtin_amdgcn_rcpf(d2[1])};
;                         const f32x2 o2 = (g2 * u2) * r2; f[4 * n + 2 * hh] = o2[0]; f[4 * n + 2 * hh + 1] = o2[1]; }
;                 u32x4 w; w.x = cvt_pk_bf16(f[0], f[1]); w.y = cvt_pk_bf16(f[2], f[3]); w.z = cvt_pk_bf16(f[4], f[5]); w.w = cvt_pk_bf16(f[6], f[7]);
;                 __builtin_nontemporal_store(w, (u32x4*)(ff + blk_off(row, col0, ldc))); }
.LBB0_795:
	s_waitcnt lgkmcnt(0)
	v_mul_f32_e32 v132, 0xbfb8aa3b, v164
	v_mul_f32_e32 v143, v164, v164
	v_pk_mul_f32 v[174:175], v[122:123], v[132:133] op_sel_hi:[1,0]
	v_pk_mul_f32 v[122:123], v[122:123], v[126:127]
	v_pk_mul_f32 v[126:127], v[114:115], v[132:133] op_sel_hi:[1,0]
	v_rcp_f32_e32 v164, v143
	v_pk_mul_f32 v[176:177], v[124:125], v[132:133] op_sel_hi:[1,0]
	v_pk_mul_f32 v[124:125], v[124:125], v[128:129]
	v_exp_f32_e32 v126, v126
	v_exp_f32_e32 v127, v127
	v_pk_mul_f32 v[128:129], v[116:117], v[132:133] op_sel_hi:[1,0]
	v_exp_f32_e32 v174, v174
	v_exp_f32_e32 v175, v175
	v_exp_f32_e32 v176, v176
	v_exp_f32_e32 v177, v177
	v_exp_f32_e32 v128, v128
	v_exp_f32_e32 v129, v129
	v_pk_fma_f32 v[126:127], v[126:127], v[164:165], v[164:165] op_sel_hi:[1,0,0]
	v_pk_fma_f32 v[174:175], v[174:175], v[164:165], v[164:165] op_sel_hi:[1,0,0]
	v_pk_fma_f32 v[176:177], v[176:177], v[164:165], v[164:165] op_sel_hi:[1,0,0]
	v_rcp_f32_e32 v126, v126
	v_rcp_f32_e32 v127, v127
	v_pk_fma_f32 v[128:129], v[128:129], v[164:165], v[164:165] op_sel_hi:[1,0,0]
	s_lshl_b32 s0, s0, 7
	v_rcp_f32_e32 v174, v174
	v_rcp_f32_e32 v175, v175
	v_rcp_f32_e32 v176, v176
	v_rcp_f32_e32 v177, v177
	v_rcp_f32_e32 v128, v128
	v_rcp_f32_e32 v129, v129
	s_or_b32 s0, s0, s75
	s_ashr_i32 s1, s1, 8
	s_ashr_i32 s0, s0, 6
	v_pk_mul_f32 v[114:115], v[114:115], v[118:119]
	s_mulk_i32 s1, 0x58
	v_pk_mul_f32 v[116:117], v[116:117], v[120:121]
	v_pk_mul_f32 v[118:119], v[114:115], v[126:127]
	s_add_i32 s6, s1, s0
	v_pk_mul_f32 v[122:123], v[122:123], v[174:175]
	v_pk_mul_f32 v[124:125], v[124:125], v[176:177]
	v_pk_mul_f32 v[120:121], v[116:117], v[128:129]
	v_cvt_pk_bf16_f32 v114, v122, v123
	v_cvt_pk_bf16_f32 v115, v124, v125
	v_cvt_pk_bf16_f32 v116, v118, v119
	s_ashr_i32 s7, s6, 31
	v_lshlrev_b32_e32 v118, 6, v154
	v_lshlrev_b32_e32 v119, 2, v154
	v_and_or_b32 v118, v118, s78, v167
	v_and_b32_e32 v119, 32, v119
	s_lshl_b64 s[6:7], s[6:7], 15
	v_bitop3_b32 v132, v118, s80, v119 bitop3:0xde
	s_add_u32 s6, s14, s6
	v_lshlrev_b32_e32 v118, 7, v154
	s_addc_u32 s7, s15, s7
	v_and_b32_e32 v118, 0x4000, v118
	v_mov_b32_e32 v119, v133
	v_lshl_add_u64 v[118:119], s[6:7], 0, v[118:119]
	v_lshl_add_u64 v[118:119], v[118:119], 0, v[132:133]
	v_cvt_pk_bf16_f32 v117, v120, v121
	global_store_dwordx4 v[118:119], v[114:117], off nt
	s_and_b64 vcc, exec, s[4:5]
	s_mov_b32 s8, s36
	v_mul_f32_e32 v114, 0xbfb8aa3b, v165
	v_mul_f32_e32 v115, v165, v165
	v_pk_mul_f32 v[118:119], v[106:107], v[114:115] op_sel_hi:[1,0]
	v_pk_mul_f32 v[106:107], v[106:107], v[110:111]
	v_pk_mul_f32 v[110:111], v[98:99], v[114:115] op_sel_hi:[1,0]
	v_rcp_f32_e32 v116, v115
	v_pk_mul_f32 v[120:121], v[108:109], v[114:115] op_sel_hi:[1,0]
	v_pk_mul_f32 v[108:109], v[108:109], v[112:113]
	v_exp_f32_e32 v110, v110
	v_exp_f32_e32 v111, v111
	v_pk_mul_f32 v[112:113], v[100:101], v[114:115] op_sel_hi:[1,0]
	v_exp_f32_e32 v118, v118
	v_exp_f32_e32 v119, v119
	v_exp_f32_e32 v120, v120
	v_exp_f32_e32 v121, v121
	v_exp_f32_e32 v112, v112
	v_exp_f32_e32 v113, v113
	v_pk_fma_f32 v[110:111], v[110:111], v[116:117], v[116:117] op_sel_hi:[1,0,0]
	v_pk_fma_f32 v[118:119], v[118:119], v[116:117], v[116:117] op_sel_hi:[1,0,0]
	v_pk_fma_f32 v[120:121], v[120:121], v[116:117], v[116:117] op_sel_hi:[1,0,0]
	v_rcp_f32_e32 v110, v110
	v_rcp_f32_e32 v111, v111
	v_pk_fma_f32 v[112:113], v[112:113], v[116:117], v[116:117] op_sel_hi:[1,0,0]
	v_rcp_f32_e32 v118, v118
	v_rcp_f32_e32 v119, v119
	v_rcp_f32_e32 v120, v120
	v_rcp_f32_e32 v121, v121
	v_rcp_f32_e32 v112, v112
	v_rcp_f32_e32 v113, v113
	v_pk_mul_f32 v[98:99], v[98:99], v[102:103]
	v_pk_mul_f32 v[100:101], v[100:101], v[104:105]
	v_pk_mul_f32 v[102:103], v[98:99], v[110:111]
	v_pk_mul_f32 v[106:107], v[106:107], v[118:119]
	v_pk_mul_f32 v[108:109], v[108:109], v[120:121]
	v_pk_mul_f32 v[104:105], v[100:101], v[112:113]
	v_cvt_pk_bf16_f32 v98, v106, v107
	v_cvt_pk_bf16_f32 v99, v108, v109
	v_cvt_pk_bf16_f32 v100, v102, v103
	v_lshrrev_b32_e32 v103, 3, v156
	v_cvt_pk_bf16_f32 v101, v104, v105
	v_lshlrev_b32_e32 v102, 6, v156
	v_and_or_b32 v103, v103, 14, s79
	v_lshlrev_b32_e32 v104, 2, v156
	v_and_or_b32 v102, v102, s78, v167
	v_lshlrev_b32_e32 v103, 10, v103
	v_and_b32_e32 v104, 32, v104
	v_bitop3_b32 v132, v102, v103, v104 bitop3:0xde
	v_lshlrev_b32_e32 v102, 7, v156
	v_and_b32_e32 v102, 0x4000, v102
	v_mov_b32_e32 v103, v133
	v_lshl_add_u64 v[102:103], s[6:7], 0, v[102:103]
	v_lshl_add_u64 v[102:103], v[102:103], 0, v[132:133]
	global_store_dwordx4 v[102:103], v[98:101], off nt
	s_mov_b64 s[44:45], s[42:43]
	s_mov_b64 s[46:47], s[40:41]
	v_mul_f32_e32 v98, 0xbfb8aa3b, v162
	v_mul_f32_e32 v99, v162, v162
	v_pk_mul_f32 v[102:103], v[90:91], v[98:99] op_sel_hi:[1,0]
	v_pk_mul_f32 v[90:91], v[90:91], v[94:95]
	v_pk_mul_f32 v[94:95], v[82:83], v[98:99] op_sel_hi:[1,0]
	v_rcp_f32_e32 v100, v99
	v_pk_mul_f32 v[104:105], v[92:93], v[98:99] op_sel_hi:[1,0]
	v_pk_mul_f32 v[92:93], v[92:93], v[96:97]
	v_exp_f32_e32 v94, v94
	v_exp_f32_e32 v95, v95
	v_pk_mul_f32 v[96:97], v[84:85], v[98:99] op_sel_hi:[1,0]
	v_exp_f32_e32 v102, v102
	v_exp_f32_e32 v103, v103
	v_exp_f32_e32 v104, v104
	v_exp_f32_e32 v105, v105
	v_exp_f32_e32 v96, v96
	v_exp_f32_e32 v97, v97
	v_pk_fma_f32 v[94:95], v[94:95], v[100:101], v[100:101] op_sel_hi:[1,0,0]
	v_pk_fma_f32 v[102:103], v[102:103], v[100:101], v[100:101] op_sel_hi:[1,0,0]
	v_pk_fma_f32 v[104:105], v[104:105], v[100:101], v[100:101] op_sel_hi:[1,0,0]
	v_rcp_f32_e32 v94, v94
	v_rcp_f32_e32 v95, v95
	v_pk_fma_f32 v[96:97], v[96:97], v[100:101], v[100:101] op_sel_hi:[1,0,0]
	v_rcp_f32_e32 v102, v102
	v_rcp_f32_e32 v103, v103
	v_rcp_f32_e32 v104, v104
	v_rcp_f32_e32 v105, v105
; __host__ __device__ __forceinline__ size_t blk_off(int row, int col, int K) { return (size_t)((row >> 8) * (K >> 6) + (col >> 6)) * 16384 + ((row >> 7) & 1) * 8192 + (lds_byte(row & 127, col & 63) >> 1); }
; __device__ __forceinline__ unsigned cvt_pk_bf16(float lo, float hi) { unsigned r; asm volatile("v_cvt_pk_bf16_f32 %0, %1, %2" : "=v"(r) : "v"(lo), "v"(hi)); return r; }
;     __device__ __forceinline__ void operator()(const f32x4 (&acc)[2][2][4][2], const Unit& u, int wr, int wc, int fr, int fq) const {
;     ...
; #pragma unroll
;         for (int ai = 0; ai < 2; ++ai)
; #pragma unroll
;             for (int m = 0; m < 4; ++m) { const int row = row0 + ai * HALF + m * 16; const float rs = rsv[ai][m];
;                 const float nl = -1.4426950408889634f * rs, ir = __builtin_amdgcn_rcpf(rs * rs);
;                 const f32x2 nl2 = {nl, nl}, ir2 = {ir, ir};
;                 float f[8];
; #pragma unroll
;                 for (int n = 0; n < 2; ++n)
; #pragma unroll
;                     for (int hh = 0; hh < 2; ++hh) { const f32x2 g2 = {acc[ai][0][m][n][2 * hh], acc[ai][0][m][n][2 * hh + 1]}, u2 = {acc[ai][1][m][n][2 * hh], acc[ai][1][m][n][2 * hh + 1]};
;                         const f32x2 t2 = g2 * nl2; const f32x2 e2 = {__builtin_amdgcn_exp2f(t2[0]), __builtin_amdgcn_exp2f(t2[1])};
;                         const f32x2 d2 = __builtin_elementwise_fma(e2, ir2, ir2); const f32x2 r2 = {__builtin_amdgcn_rcpf(d2[0]), __builtin_amdgcn_rcpf(d2[1])};
;                         const f32x2 o2 = (g2 * u2) * r2; f[4 * n + 2 * hh] = o2[0]; f[4 * n + 2 * hh + 1] = o2[1]; }
;                 u32x4 w; w.x = cvt_pk_bf16(f[0], f[1]); w.y = cvt_pk_bf16(f[2], f[3]); w.z = cvt_pk_bf16(f[4], f[5]); w.w = cvt_pk_bf16(f[6], f[7]);
;                 __builtin_nontemporal_store(w, (u32x4*)(ff + blk_off(row, col0, ldc))); }
	v_rcp_f32_e32 v96, v96
	v_rcp_f32_e32 v97, v97
	v_pk_mul_f32 v[82:83], v[82:83], v[86:87]
	v_pk_mul_f32 v[84:85], v[84:85], v[88:89]
	v_pk_mul_f32 v[86:87], v[82:83], v[94:95]
	v_pk_mul_f32 v[90:91], v[90:91], v[102:103]
	v_pk_mul_f32 v[92:93], v[92:93], v[104:105]
	v_pk_mul_f32 v[88:89], v[84:85], v[96:97]
	v_cvt_pk_bf16_f32 v82, v90, v91
	v_cvt_pk_bf16_f32 v83, v92, v93
	v_cvt_pk_bf16_f32 v84, v86, v87
	v_lshrrev_b32_e32 v87, 3, v152
	v_cvt_pk_bf16_f32 v85, v88, v89
	v_lshlrev_b32_e32 v86, 6, v152
	v_and_or_b32 v87, v87, 14, s79
	v_lshlrev_b32_e32 v88, 2, v152
	v_and_or_b32 v86, v86, s78, v167
	v_lshlrev_b32_e32 v87, 10, v87
	v_and_b32_e32 v88, 32, v88
	v_bitop3_b32 v132, v86, v87, v88 bitop3:0xde
	v_lshlrev_b32_e32 v86, 7, v152
	v_and_b32_e32 v86, 0x4000, v86
	v_mov_b32_e32 v87, v133
	v_lshl_add_u64 v[86:87], s[6:7], 0, v[86:87]
	v_lshl_add_u64 v[86:87], v[86:87], 0, v[132:133]
	global_store_dwordx4 v[86:87], v[82:85], off nt
	s_nop 1
	v_mul_f32_e32 v82, 0xbfb8aa3b, v163
	v_mul_f32_e32 v83, v163, v163
	v_pk_mul_f32 v[86:87], v[74:75], v[82:83] op_sel_hi:[1,0]
	v_pk_mul_f32 v[74:75], v[74:75], v[78:79]
	v_pk_mul_f32 v[78:79], v[62:63], v[82:83] op_sel_hi:[1,0]
	v_rcp_f32_e32 v84, v83
	v_pk_mul_f32 v[88:89], v[76:77], v[82:83] op_sel_hi:[1,0]
	v_pk_mul_f32 v[76:77], v[76:77], v[80:81]
	v_exp_f32_e32 v78, v78
	v_exp_f32_e32 v79, v79
	v_pk_mul_f32 v[80:81], v[64:65], v[82:83] op_sel_hi:[1,0]
	v_exp_f32_e32 v86, v86
	v_exp_f32_e32 v87, v87
	v_exp_f32_e32 v88, v88
	v_exp_f32_e32 v89, v89
	v_exp_f32_e32 v80, v80
	v_exp_f32_e32 v81, v81
	v_pk_fma_f32 v[78:79], v[78:79], v[84:85], v[84:85] op_sel_hi:[1,0,0]
	v_pk_fma_f32 v[86:87], v[86:87], v[84:85], v[84:85] op_sel_hi:[1,0,0]
	v_pk_fma_f32 v[88:89], v[88:89], v[84:85], v[84:85] op_sel_hi:[1,0,0]
	v_rcp_f32_e32 v78, v78
	v_rcp_f32_e32 v79, v79
	v_pk_fma_f32 v[80:81], v[80:81], v[84:85], v[84:85] op_sel_hi:[1,0,0]
	v_rcp_f32_e32 v86, v86
	v_rcp_f32_e32 v87, v87
	v_rcp_f32_e32 v88, v88
	v_rcp_f32_e32 v89, v89
	v_rcp_f32_e32 v80, v80
	v_rcp_f32_e32 v81, v81
	v_pk_mul_f32 v[62:63], v[62:63], v[70:71]
	v_pk_mul_f32 v[64:65], v[64:65], v[72:73]
	v_pk_mul_f32 v[70:71], v[62:63], v[78:79]
	v_pk_mul_f32 v[74:75], v[74:75], v[86:87]
	v_pk_mul_f32 v[76:77], v[76:77], v[88:89]
	v_pk_mul_f32 v[72:73], v[64:65], v[80:81]
	v_cvt_pk_bf16_f32 v62, v74, v75
	v_cvt_pk_bf16_f32 v63, v76, v77
	v_cvt_pk_bf16_f32 v64, v70, v71
	v_lshrrev_b32_e32 v71, 3, v142
	v_cvt_pk_bf16_f32 v65, v72, v73
	v_lshlrev_b32_e32 v70, 6, v142
	v_and_or_b32 v71, v71, 14, s79
	v_lshlrev_b32_e32 v72, 2, v142
	v_and_or_b32 v70, v70, s78, v167
	v_lshlrev_b32_e32 v71, 10, v71
	v_and_b32_e32 v72, 32, v72
	v_bitop3_b32 v132, v70, v71, v72 bitop3:0xde
	v_lshlrev_b32_e32 v70, 7, v142
	v_and_b32_e32 v70, 0x4000, v70
	v_mov_b32_e32 v71, v133
	v_lshl_add_u64 v[70:71], s[6:7], 0, v[70:71]
	v_lshl_add_u64 v[70:71], v[70:71], 0, v[132:133]
	global_store_dwordx4 v[70:71], v[62:65], off nt
	s_nop 1
	v_mul_f32_e32 v62, 0xbfb8aa3b, v160
	v_mul_f32_e32 v63, v160, v160
	v_rcp_f32_e32 v64, v63
	v_pk_mul_f32 v[70:71], v[58:59], v[62:63] op_sel_hi:[1,0]
	v_pk_mul_f32 v[72:73], v[60:61], v[62:63] op_sel_hi:[1,0]
	v_pk_mul_f32 v[58:59], v[58:59], v[66:67]
	v_pk_mul_f32 v[66:67], v[50:51], v[62:63] op_sel_hi:[1,0]
	v_pk_mul_f32 v[62:63], v[52:53], v[62:63] op_sel_hi:[1,0]
	v_exp_f32_e32 v66, v66
	v_exp_f32_e32 v67, v67
	v_exp_f32_e32 v62, v62
	v_exp_f32_e32 v63, v63
	v_exp_f32_e32 v70, v70
	v_exp_f32_e32 v71, v71
	v_exp_f32_e32 v72, v72
	v_exp_f32_e32 v73, v73
	v_lshrrev_b32_e32 v65, 8, v150
	v_pk_fma_f32 v[66:67], v[66:67], v[64:65], v[64:65] op_sel_hi:[1,0,0]
	v_pk_fma_f32 v[62:63], v[62:63], v[64:65], v[64:65] op_sel_hi:[1,0,0]
	v_pk_fma_f32 v[70:71], v[70:71], v[64:65], v[64:65] op_sel_hi:[1,0,0]
	v_pk_fma_f32 v[72:73], v[72:73], v[64:65], v[64:65] op_sel_hi:[1,0,0]
	v_rcp_f32_e32 v66, v66
	v_rcp_f32_e32 v67, v67
	v_rcp_f32_e32 v62, v62
	v_rcp_f32_e32 v63, v63
	v_rcp_f32_e32 v70, v70
	v_rcp_f32_e32 v71, v71
	v_rcp_f32_e32 v72, v72
	v_rcp_f32_e32 v73, v73
	v_pk_mul_f32 v[52:53], v[52:53], v[56:57]
	v_pk_mul_f32 v[50:51], v[50:51], v[54:55]
	v_pk_mul_f32 v[60:61], v[60:61], v[68:69]
	v_pk_mul_f32 v[50:51], v[50:51], v[66:67]
	v_pk_mul_f32 v[56:57], v[52:53], v[62:63]
	v_pk_mul_f32 v[58:59], v[58:59], v[70:71]
	v_pk_mul_f32 v[60:61], v[60:61], v[72:73]
	v_cvt_pk_bf16_f32 v52, v58, v59
	v_lshlrev_b32_e32 v58, 2, v150
	v_cvt_pk_bf16_f32 v53, v60, v61
	v_cvt_pk_bf16_f32 v54, v50, v51
	v_cvt_pk_bf16_f32 v55, v56, v57
	v_mov_b32_e32 v50, s0
	v_lshrrev_b32_e32 v57, 3, v150
	v_mad_i32_i24 v50, v65, s85, v50
	v_lshlrev_b32_e32 v56, 6, v150
	v_and_or_b32 v57, v57, 14, s79
	v_ashrrev_i32_e32 v51, 31, v50
	v_and_or_b32 v56, v56, s78, v167
	v_lshlrev_b32_e32 v57, 10, v57
	v_and_b32_e32 v58, 32, v58
	v_bitop3_b32 v132, v56, v57, v58 bitop3:0xde
	v_lshlrev_b64 v[50:51], 15, v[50:51]
	v_lshlrev_b32_e32 v56, 7, v150
	v_lshl_add_u64 v[50:51], s[14:15], 0, v[50:51]
	v_and_b32_e32 v56, 0x4000, v56
	v_mov_b32_e32 v57, v133
	v_lshl_add_u64 v[56:57], v[50:51], 0, v[56:57]
	v_lshl_add_u64 v[56:57], v[56:57], 0, v[132:133]
	global_store_dwordx4 v[56:57], v[52:55], off nt
	s_mov_b32 s0, s38
	s_nop 0
	v_mul_f32_e32 v52, 0xbfb8aa3b, v161
	v_mul_f32_e32 v53, v161, v161
	v_pk_mul_f32 v[56:57], v[42:43], v[52:53] op_sel_hi:[1,0]
	v_pk_mul_f32 v[42:43], v[42:43], v[46:47]
	v_pk_mul_f32 v[46:47], v[34:35], v[52:53] op_sel_hi:[1,0]
	v_rcp_f32_e32 v54, v53
	v_pk_mul_f32 v[58:59], v[44:45], v[52:53] op_sel_hi:[1,0]
	v_pk_mul_f32 v[44:45], v[44:45], v[48:49]
	v_exp_f32_e32 v46, v46
	v_exp_f32_e32 v47, v47
; __host__ __device__ __forceinline__ size_t blk_off(int row, int col, int K) { return (size_t)((row >> 8) * (K >> 6) + (col >> 6)) * 16384 + ((row >> 7) & 1) * 8192 + (lds_byte(row & 127, col & 63) >> 1); }
; __device__ __forceinline__ unsigned cvt_pk_bf16(float lo, float hi) { unsigned r; asm volatile("v_cvt_pk_bf16_f32 %0, %1, %2" : "=v"(r) : "v"(lo), "v"(hi)); return r; }
;     __device__ __forceinline__ void operator()(const f32x4 (&acc)[2][2][4][2], const Unit& u, int wr, int wc, int fr, int fq) const {
;     ...
; #pragma unroll
;         for (int ai = 0; ai < 2; ++ai)
; #pragma unroll
;             for (int m = 0; m < 4; ++m) { const int row = row0 + ai * HALF + m * 16; const float rs = rsv[ai][m];
;                 const float nl = -1.4426950408889634f * rs, ir = __builtin_amdgcn_rcpf(rs * rs);
;                 const f32x2 nl2 = {nl, nl}, ir2 = {ir, ir};
;                 float f[8];
; #pragma unroll
;                 for (int n = 0; n < 2; ++n)
; #pragma unroll
;                     for (int hh = 0; hh < 2; ++hh) { const f32x2 g2 = {acc[ai][0][m][n][2 * hh], acc[ai][0][m][n][2 * hh + 1]}, u2 = {acc[ai][1][m][n][2 * hh], acc[ai][1][m][n][2 * hh + 1]};
;                         const f32x2 t2 = g2 * nl2; const f32x2 e2 = {__builtin_amdgcn_exp2f(t2[0]), __builtin_amdgcn_exp2f(t2[1])};
;                         const f32x2 d2 = __builtin_elementwise_fma(e2, ir2, ir2); const f32x2 r2 = {__builtin_amdgcn_rcpf(d2[0]), __builtin_amdgcn_rcpf(d2[1])};
;                         const f32x2 o2 = (g2 * u2) * r2; f[4 * n + 2 * hh] = o2[0]; f[4 * n + 2 * hh + 1] = o2[1]; }
;                 u32x4 w; w.x = cvt_pk_bf16(f[0], f[1]); w.y = cvt_pk_bf16(f[2], f[3]); w.z = cvt_pk_bf16(f[4], f[5]); w.w = cvt_pk_bf16(f[6], f[7]);
;                 __builtin_nontemporal_store(w, (u32x4*)(ff + blk_off(row, col0, ldc))); }
	v_pk_mul_f32 v[48:49], v[36:37], v[52:53] op_sel_hi:[1,0]
	v_exp_f32_e32 v56, v56
	v_exp_f32_e32 v57, v57
	v_exp_f32_e32 v58, v58
	v_exp_f32_e32 v59, v59
	v_exp_f32_e32 v48, v48
	v_exp_f32_e32 v49, v49
	v_pk_fma_f32 v[46:47], v[46:47], v[54:55], v[54:55] op_sel_hi:[1,0,0]
	v_pk_fma_f32 v[56:57], v[56:57], v[54:55], v[54:55] op_sel_hi:[1,0,0]
	v_pk_fma_f32 v[58:59], v[58:59], v[54:55], v[54:55] op_sel_hi:[1,0,0]
	v_rcp_f32_e32 v46, v46
	v_rcp_f32_e32 v47, v47
	v_pk_fma_f32 v[48:49], v[48:49], v[54:55], v[54:55] op_sel_hi:[1,0,0]
	v_rcp_f32_e32 v56, v56
	v_rcp_f32_e32 v57, v57
	v_rcp_f32_e32 v58, v58
	v_rcp_f32_e32 v59, v59
	v_rcp_f32_e32 v48, v48
	v_rcp_f32_e32 v49, v49
	v_pk_mul_f32 v[34:35], v[34:35], v[38:39]
	v_pk_mul_f32 v[36:37], v[36:37], v[40:41]
	v_pk_mul_f32 v[38:39], v[34:35], v[46:47]
	v_pk_mul_f32 v[42:43], v[42:43], v[56:57]
	v_pk_mul_f32 v[44:45], v[44:45], v[58:59]
	v_pk_mul_f32 v[40:41], v[36:37], v[48:49]
	v_cvt_pk_bf16_f32 v34, v42, v43
	v_cvt_pk_bf16_f32 v35, v44, v45
	v_cvt_pk_bf16_f32 v36, v38, v39
	v_lshrrev_b32_e32 v39, 3, v148
	v_cvt_pk_bf16_f32 v37, v40, v41
	v_lshlrev_b32_e32 v38, 6, v148
	v_and_or_b32 v39, v39, 14, s79
	v_lshlrev_b32_e32 v40, 2, v148
	v_and_or_b32 v38, v38, s78, v167
	v_lshlrev_b32_e32 v39, 10, v39
	v_and_b32_e32 v40, 32, v40
	v_bitop3_b32 v132, v38, v39, v40 bitop3:0xde
	v_lshlrev_b32_e32 v38, 7, v148
	v_and_b32_e32 v38, 0x4000, v38
	v_mov_b32_e32 v39, v133
	v_lshl_add_u64 v[38:39], v[50:51], 0, v[38:39]
	v_lshl_add_u64 v[38:39], v[38:39], 0, v[132:133]
	global_store_dwordx4 v[38:39], v[34:37], off nt
	s_nop 1
	v_mul_f32_e32 v34, 0xbfb8aa3b, v158
	v_mul_f32_e32 v35, v158, v158
	v_pk_mul_f32 v[38:39], v[26:27], v[34:35] op_sel_hi:[1,0]
	v_pk_mul_f32 v[26:27], v[26:27], v[30:31]
	v_pk_mul_f32 v[30:31], v[18:19], v[34:35] op_sel_hi:[1,0]
	v_rcp_f32_e32 v36, v35
	v_pk_mul_f32 v[40:41], v[28:29], v[34:35] op_sel_hi:[1,0]
	v_pk_mul_f32 v[28:29], v[28:29], v[32:33]
	v_exp_f32_e32 v30, v30
	v_exp_f32_e32 v31, v31
	v_pk_mul_f32 v[32:33], v[20:21], v[34:35] op_sel_hi:[1,0]
	v_exp_f32_e32 v38, v38
	v_exp_f32_e32 v39, v39
	v_exp_f32_e32 v40, v40
	v_exp_f32_e32 v41, v41
	v_exp_f32_e32 v32, v32
	v_exp_f32_e32 v33, v33
	v_pk_fma_f32 v[30:31], v[30:31], v[36:37], v[36:37] op_sel_hi:[1,0,0]
	v_pk_fma_f32 v[38:39], v[38:39], v[36:37], v[36:37] op_sel_hi:[1,0,0]
	v_pk_fma_f32 v[40:41], v[40:41], v[36:37], v[36:37] op_sel_hi:[1,0,0]
	v_rcp_f32_e32 v30, v30
	v_rcp_f32_e32 v31, v31
	v_pk_fma_f32 v[32:33], v[32:33], v[36:37], v[36:37] op_sel_hi:[1,0,0]
	v_rcp_f32_e32 v38, v38
	v_rcp_f32_e32 v39, v39
	v_rcp_f32_e32 v40, v40
	v_rcp_f32_e32 v41, v41
	v_rcp_f32_e32 v32, v32
	v_rcp_f32_e32 v33, v33
	v_pk_mul_f32 v[18:19], v[18:19], v[22:23]
	v_pk_mul_f32 v[20:21], v[20:21], v[24:25]
	v_pk_mul_f32 v[22:23], v[18:19], v[30:31]
	v_pk_mul_f32 v[26:27], v[26:27], v[38:39]
	v_pk_mul_f32 v[28:29], v[28:29], v[40:41]
	v_pk_mul_f32 v[24:25], v[20:21], v[32:33]
	v_cvt_pk_bf16_f32 v18, v26, v27
	v_cvt_pk_bf16_f32 v19, v28, v29
	v_cvt_pk_bf16_f32 v20, v22, v23
	v_lshrrev_b32_e32 v23, 3, v146
	v_cvt_pk_bf16_f32 v21, v24, v25
	v_lshlrev_b32_e32 v22, 6, v146
	v_and_or_b32 v23, v23, 14, s79
	v_lshlrev_b32_e32 v24, 2, v146
	v_and_or_b32 v22, v22, s78, v167
	v_lshlrev_b32_e32 v23, 10, v23
	v_and_b32_e32 v24, 32, v24
	v_bitop3_b32 v132, v22, v23, v24 bitop3:0xde
	v_lshlrev_b32_e32 v22, 7, v146
	v_and_b32_e32 v22, 0x4000, v22
	v_mov_b32_e32 v23, v133
	v_lshl_add_u64 v[22:23], v[50:51], 0, v[22:23]
	v_lshl_add_u64 v[22:23], v[22:23], 0, v[132:133]
	global_store_dwordx4 v[22:23], v[18:21], off nt
	s_nop 1
	v_mul_f32_e32 v18, 0xbfb8aa3b, v159
	v_mul_f32_e32 v19, v159, v159
	v_pk_mul_f32 v[22:23], v[10:11], v[18:19] op_sel_hi:[1,0]
	v_pk_mul_f32 v[10:11], v[10:11], v[14:15]
	v_pk_mul_f32 v[14:15], v[2:3], v[18:19] op_sel_hi:[1,0]
	v_rcp_f32_e32 v20, v19
	v_pk_mul_f32 v[24:25], v[12:13], v[18:19] op_sel_hi:[1,0]
	v_pk_mul_f32 v[12:13], v[12:13], v[16:17]
	v_exp_f32_e32 v14, v14
	v_exp_f32_e32 v15, v15
	v_pk_mul_f32 v[16:17], v[4:5], v[18:19] op_sel_hi:[1,0]
	v_exp_f32_e32 v22, v22
	v_exp_f32_e32 v23, v23
	v_exp_f32_e32 v24, v24
	v_exp_f32_e32 v25, v25
	v_exp_f32_e32 v16, v16
	v_exp_f32_e32 v17, v17
	v_pk_fma_f32 v[14:15], v[14:15], v[20:21], v[20:21] op_sel_hi:[1,0,0]
	v_pk_fma_f32 v[22:23], v[22:23], v[20:21], v[20:21] op_sel_hi:[1,0,0]
	v_pk_fma_f32 v[24:25], v[24:25], v[20:21], v[20:21] op_sel_hi:[1,0,0]
	v_rcp_f32_e32 v14, v14
	v_rcp_f32_e32 v15, v15
	v_pk_fma_f32 v[16:17], v[16:17], v[20:21], v[20:21] op_sel_hi:[1,0,0]
	v_rcp_f32_e32 v22, v22
	v_rcp_f32_e32 v23, v23
	v_rcp_f32_e32 v24, v24
	v_rcp_f32_e32 v25, v25
	v_rcp_f32_e32 v16, v16
	v_rcp_f32_e32 v17, v17
	v_pk_mul_f32 v[2:3], v[2:3], v[6:7]
	v_pk_mul_f32 v[4:5], v[4:5], v[8:9]
	v_pk_mul_f32 v[6:7], v[2:3], v[14:15]
	v_pk_mul_f32 v[10:11], v[10:11], v[22:23]
	v_pk_mul_f32 v[12:13], v[12:13], v[24:25]
	v_pk_mul_f32 v[8:9], v[4:5], v[16:17]
	v_cvt_pk_bf16_f32 v2, v10, v11
	v_cvt_pk_bf16_f32 v3, v12, v13
	v_cvt_pk_bf16_f32 v4, v6, v7
	v_lshrrev_b32_e32 v7, 3, v144
	v_cvt_pk_bf16_f32 v5, v8, v9
	v_lshlrev_b32_e32 v6, 6, v144
	v_and_or_b32 v7, v7, 14, s79
	v_lshlrev_b32_e32 v8, 2, v144
	v_and_or_b32 v6, v6, s78, v167
	v_lshlrev_b32_e32 v7, 10, v7
	v_and_b32_e32 v8, 32, v8
	v_bitop3_b32 v132, v6, v7, v8 bitop3:0xde
	v_lshlrev_b32_e32 v6, 7, v144
	v_and_b32_e32 v6, 0x4000, v6
	v_mov_b32_e32 v7, v133
	v_lshl_add_u64 v[6:7], v[50:51], 0, v[6:7]
	v_lshl_add_u64 v[6:7], v[6:7], 0, v[132:133]
	global_store_dwordx4 v[6:7], v[2:5], off nt
	s_cmpk_gt_u32 s51, 0xff
	s_cbranch_scc0 .Lgu_ae1
	s_barrier
.Lgu_ae1:
	s_cbranch_vccnz .LBB0_804

.LBB0_799:
	ds_read_b128 v[144:147], v168
	ds_read_b128 v[148:151], v168 offset:1024
	ds_read_b128 v[152:155], v168 offset:2048
	ds_read_b128 v[156:159], v168 offset:3072
	ds_read_b128 v[160:163], v169
	ds_read_b128 v[174:177], v169 offset:1024
	ds_read_b128 v[178:181], v169 offset:2048
	ds_read_b128 v[184:187], v169 offset:3072
	s_cmp_eq_u32 s60, 28
	s_cselect_b32 s97, s1, s7
	s_cselect_b32 s96, s9, s6
	s_cselect_b32 s45, s37, s47
	s_cselect_b32 s44, s39, s46
	v_lshl_add_u64 v[164:165], s[6:7], 0, v[130:131]
	s_mov_b32 m0, s86
	v_lshl_add_u64 v[220:221], v[164:165], 0, s[28:29]
	ds_read_b128 v[188:191], v170
	ds_read_b128 v[192:195], v170 offset:1024
	ds_read_b128 v[196:199], v170 offset:2048
	ds_read_b128 v[200:203], v170 offset:3072
	ds_read_b128 v[204:207], v170 offset:4096
	ds_read_b128 v[208:211], v170 offset:5120
	ds_read_b128 v[212:215], v170 offset:6144
	ds_read_b128 v[216:219], v170 offset:7168
	global_load_lds_dwordx4 v[220:221], off
	v_lshl_add_u64 v[164:165], v[164:165], 0, s[30:31]
	s_mov_b32 m0, s87
	s_nop 0
	global_load_lds_dwordx4 v[164:165], off
	s_waitcnt vmcnt(8)
	s_waitcnt lgkmcnt(0)
	s_barrier
	s_setprio 1
	s_waitcnt lgkmcnt(0)
	v_mfma_f32_16x16x32_bf16 v[122:125], v[144:147], v[188:191], v[122:125]
	v_mfma_f32_16x16x32_bf16 v[114:117], v[152:155], v[188:191], v[114:117]
	v_mfma_f32_16x16x32_bf16 v[106:109], v[144:147], v[196:199], v[106:109]
	v_mfma_f32_16x16x32_bf16 v[98:101], v[152:155], v[196:199], v[98:101]
	v_mfma_f32_16x16x32_bf16 v[90:93], v[144:147], v[204:207], v[90:93]
	v_mfma_f32_16x16x32_bf16 v[82:85], v[152:155], v[204:207], v[82:85]
	v_mfma_f32_16x16x32_bf16 v[74:77], v[144:147], v[212:215], v[74:77]
	v_mfma_f32_16x16x32_bf16 v[62:65], v[152:155], v[212:215], v[62:65]
	v_mfma_f32_16x16x32_bf16 v[122:125], v[148:151], v[192:195], v[122:125]
	v_mfma_f32_16x16x32_bf16 v[114:117], v[156:159], v[192:195], v[114:117]
	v_mfma_f32_16x16x32_bf16 v[106:109], v[148:151], v[200:203], v[106:109]
	v_mfma_f32_16x16x32_bf16 v[98:101], v[156:159], v[200:203], v[98:101]
	v_mfma_f32_16x16x32_bf16 v[90:93], v[148:151], v[208:211], v[90:93]
	v_mfma_f32_16x16x32_bf16 v[82:85], v[156:159], v[208:211], v[82:85]
	v_mfma_f32_16x16x32_bf16 v[74:77], v[148:151], v[216:219], v[74:77]
	v_mfma_f32_16x16x32_bf16 v[62:65], v[156:159], v[216:219], v[62:65]
	s_setprio 0
	s_setprio 1
	v_mfma_f32_16x16x32_bf16 v[126:129], v[160:163], v[188:191], v[126:129]
	v_mfma_f32_16x16x32_bf16 v[118:121], v[178:181], v[188:191], v[118:121]
	v_mfma_f32_16x16x32_bf16 v[110:113], v[160:163], v[196:199], v[110:113]
	v_mfma_f32_16x16x32_bf16 v[102:105], v[178:181], v[196:199], v[102:105]
	v_mfma_f32_16x16x32_bf16 v[94:97], v[160:163], v[204:207], v[94:97]
	v_mfma_f32_16x16x32_bf16 v[86:89], v[178:181], v[204:207], v[86:89]
	v_mfma_f32_16x16x32_bf16 v[78:81], v[160:163], v[212:215], v[78:81]
	v_mfma_f32_16x16x32_bf16 v[70:73], v[178:181], v[212:215], v[70:73]
	v_mfma_f32_16x16x32_bf16 v[126:129], v[174:177], v[192:195], v[126:129]
	v_mfma_f32_16x16x32_bf16 v[118:121], v[184:187], v[192:195], v[118:121]
	v_mfma_f32_16x16x32_bf16 v[110:113], v[174:177], v[200:203], v[110:113]
	v_mfma_f32_16x16x32_bf16 v[102:105], v[184:187], v[200:203], v[102:105]
	v_mfma_f32_16x16x32_bf16 v[94:97], v[174:177], v[208:211], v[94:97]
	v_mfma_f32_16x16x32_bf16 v[86:89], v[184:187], v[208:211], v[86:89]
	v_mfma_f32_16x16x32_bf16 v[78:81], v[174:177], v[216:219], v[78:81]
	v_mfma_f32_16x16x32_bf16 v[70:73], v[184:187], v[216:219], v[70:73]
	s_setprio 0
	s_barrier
	s_mov_b32 m0, s88
	v_lshl_add_u64 v[164:165], s[44:45], 0, v[130:131]
	ds_read_b128 v[188:191], v170 offset:16384
	ds_read_b128 v[192:195], v170 offset:17408
	ds_read_b128 v[196:199], v170 offset:18432
	ds_read_b128 v[200:203], v170 offset:19456
	ds_read_b128 v[204:207], v170 offset:20480
	ds_read_b128 v[208:211], v170 offset:21504
	ds_read_b128 v[212:215], v170 offset:22528
	ds_read_b128 v[216:219], v170 offset:23552
	global_load_lds_dwordx4 v[164:165], off
	v_lshl_add_u64 v[220:221], v[164:165], 0, s[10:11]
	s_mov_b32 m0, s89
	v_lshl_add_u64 v[164:165], v[164:165], 0, s[12:13]
	global_load_lds_dwordx4 v[220:221], off
	v_lshl_add_u64 v[220:221], s[44:45], 0, v[134:135]
	s_mov_b32 m0, s90
	s_nop 0
	global_load_lds_dwordx4 v[220:221], off
	s_mov_b32 m0, s91
	s_nop 0
	global_load_lds_dwordx4 v[164:165], off
	v_lshl_add_u64 v[164:165], s[96:97], 0, v[130:131]
	s_mov_b32 m0, s69
	v_lshl_add_u64 v[220:221], v[164:165], 0, s[10:11]
	global_load_lds_dwordx4 v[164:165], off
	s_mov_b32 m0, s70
	s_nop 0
	global_load_lds_dwordx4 v[220:221], off
	s_waitcnt vmcnt(8)
	s_waitcnt lgkmcnt(0)
	s_barrier
	s_setprio 1
	s_waitcnt lgkmcnt(0)
	v_mfma_f32_16x16x32_bf16 v[58:61], v[144:147], v[188:191], v[58:61]
	v_mfma_f32_16x16x32_bf16 v[50:53], v[152:155], v[188:191], v[50:53]
	v_mfma_f32_16x16x32_bf16 v[42:45], v[144:147], v[196:199], v[42:45]
	v_mfma_f32_16x16x32_bf16 v[34:37], v[152:155], v[196:199], v[34:37]
	v_mfma_f32_16x16x32_bf16 v[26:29], v[144:147], v[204:207], v[26:29]
	v_mfma_f32_16x16x32_bf16 v[18:21], v[152:155], v[204:207], v[18:21]
	v_mfma_f32_16x16x32_bf16 v[10:13], v[144:147], v[212:215], v[10:13]
	v_mfma_f32_16x16x32_bf16 v[2:5], v[152:155], v[212:215], v[2:5]
	v_mfma_f32_16x16x32_bf16 v[58:61], v[148:151], v[192:195], v[58:61]
	v_mfma_f32_16x16x32_bf16 v[50:53], v[156:159], v[192:195], v[50:53]
	v_mfma_f32_16x16x32_bf16 v[42:45], v[148:151], v[200:203], v[42:45]
	v_mfma_f32_16x16x32_bf16 v[34:37], v[156:159], v[200:203], v[34:37]
	v_mfma_f32_16x16x32_bf16 v[26:29], v[148:151], v[208:211], v[26:29]
	v_mfma_f32_16x16x32_bf16 v[18:21], v[156:159], v[208:211], v[18:21]
	v_mfma_f32_16x16x32_bf16 v[10:13], v[148:151], v[216:219], v[10:13]
	v_mfma_f32_16x16x32_bf16 v[2:5], v[156:159], v[216:219], v[2:5]
	s_setprio 0
	s_setprio 1
	v_mfma_f32_16x16x32_bf16 v[66:69], v[160:163], v[188:191], v[66:69]
	v_mfma_f32_16x16x32_bf16 v[54:57], v[178:181], v[188:191], v[54:57]
	v_mfma_f32_16x16x32_bf16 v[46:49], v[160:163], v[196:199], v[46:49]
	v_mfma_f32_16x16x32_bf16 v[38:41], v[178:181], v[196:199], v[38:41]
	v_mfma_f32_16x16x32_bf16 v[30:33], v[160:163], v[204:207], v[30:33]
	v_mfma_f32_16x16x32_bf16 v[22:25], v[178:181], v[204:207], v[22:25]
	v_mfma_f32_16x16x32_bf16 v[14:17], v[160:163], v[212:215], v[14:17]
	v_mfma_f32_16x16x32_bf16 v[6:9], v[178:181], v[212:215], v[6:9]
	v_mfma_f32_16x16x32_bf16 v[66:69], v[174:177], v[192:195], v[66:69]
	v_mfma_f32_16x16x32_bf16 v[54:57], v[184:187], v[192:195], v[54:57]
	v_mfma_f32_16x16x32_bf16 v[46:49], v[174:177], v[200:203], v[46:49]
	v_mfma_f32_16x16x32_bf16 v[38:41], v[184:187], v[200:203], v[38:41]
	v_mfma_f32_16x16x32_bf16 v[30:33], v[174:177], v[208:211], v[30:33]
	v_mfma_f32_16x16x32_bf16 v[22:25], v[184:187], v[208:211], v[22:25]
	v_mfma_f32_16x16x32_bf16 v[14:17], v[174:177], v[216:219], v[14:17]
	v_mfma_f32_16x16x32_bf16 v[6:9], v[184:187], v[216:219], v[6:9]
	s_setprio 0
	s_barrier
	ds_read_b128 v[144:147], v132
	ds_read_b128 v[148:151], v132 offset:1024
	ds_read_b128 v[152:155], v132 offset:2048
	ds_read_b128 v[156:159], v132 offset:3072
	ds_read_b128 v[160:163], v142
	ds_read_b128 v[174:177], v142 offset:1024
	ds_read_b128 v[178:181], v142 offset:2048
	ds_read_b128 v[184:187], v142 offset:3072
	s_mov_b64 s[96:97], 0x4000
	s_mov_b32 m0, s71
	v_lshl_add_u64 v[220:221], v[164:165], 0, s[96:97]
	ds_read_b128 v[188:191], v170 offset:32768
	ds_read_b128 v[192:195], v170 offset:33792
	ds_read_b128 v[196:199], v170 offset:34816
	ds_read_b128 v[200:203], v170 offset:35840
	ds_read_b128 v[204:207], v170 offset:36864
	ds_read_b128 v[208:211], v170 offset:37888
	ds_read_b128 v[212:215], v170 offset:38912
	ds_read_b128 v[216:219], v170 offset:39936
	global_load_lds_dwordx4 v[220:221], off
	v_lshl_add_u64 v[220:221], v[164:165], 0, s[12:13]
	s_mov_b32 m0, s72
	s_nop 0
	global_load_lds_dwordx4 v[220:221], off
	s_waitcnt vmcnt(8)
	s_waitcnt lgkmcnt(0)
	s_barrier
	s_setprio 1
	s_waitcnt lgkmcnt(0)
	v_mfma_f32_16x16x32_bf16 v[122:125], v[144:147], v[188:191], v[122:125]
	v_mfma_f32_16x16x32_bf16 v[114:117], v[152:155], v[188:191], v[114:117]
	v_mfma_f32_16x16x32_bf16 v[106:109], v[144:147], v[196:199], v[106:109]
	v_mfma_f32_16x16x32_bf16 v[98:101], v[152:155], v[196:199], v[98:101]
	v_mfma_f32_16x16x32_bf16 v[90:93], v[144:147], v[204:207], v[90:93]
	v_mfma_f32_16x16x32_bf16 v[82:85], v[152:155], v[204:207], v[82:85]
	v_mfma_f32_16x16x32_bf16 v[74:77], v[144:147], v[212:215], v[74:77]
	v_mfma_f32_16x16x32_bf16 v[62:65], v[152:155], v[212:215], v[62:65]
	v_mfma_f32_16x16x32_bf16 v[122:125], v[148:151], v[192:195], v[122:125]
	v_mfma_f32_16x16x32_bf16 v[114:117], v[156:159], v[192:195], v[114:117]
	v_mfma_f32_16x16x32_bf16 v[106:109], v[148:151], v[200:203], v[106:109]
	v_mfma_f32_16x16x32_bf16 v[98:101], v[156:159], v[200:203], v[98:101]
	v_mfma_f32_16x16x32_bf16 v[90:93], v[148:151], v[208:211], v[90:93]
	v_mfma_f32_16x16x32_bf16 v[82:85], v[156:159], v[208:211], v[82:85]
	v_mfma_f32_16x16x32_bf16 v[74:77], v[148:151], v[216:219], v[74:77]
	v_mfma_f32_16x16x32_bf16 v[62:65], v[156:159], v[216:219], v[62:65]
	s_setprio 0
	s_setprio 1
	v_mfma_f32_16x16x32_bf16 v[126:129], v[160:163], v[188:191], v[126:129]
	v_mfma_f32_16x16x32_bf16 v[118:121], v[178:181], v[188:191], v[118:121]
	v_mfma_f32_16x16x32_bf16 v[110:113], v[160:163], v[196:199], v[110:113]
	v_mfma_f32_16x16x32_bf16 v[102:105], v[178:181], v[196:199], v[102:105]
	v_mfma_f32_16x16x32_bf16 v[94:97], v[160:163], v[204:207], v[94:97]
	v_mfma_f32_16x16x32_bf16 v[86:89], v[178:181], v[204:207], v[86:89]
	v_mfma_f32_16x16x32_bf16 v[78:81], v[160:163], v[212:215], v[78:81]
	v_mfma_f32_16x16x32_bf16 v[70:73], v[178:181], v[212:215], v[70:73]
	v_mfma_f32_16x16x32_bf16 v[126:129], v[174:177], v[192:195], v[126:129]
	v_mfma_f32_16x16x32_bf16 v[118:121], v[184:187], v[192:195], v[118:121]
	v_mfma_f32_16x16x32_bf16 v[110:113], v[174:177], v[200:203], v[110:113]
	v_mfma_f32_16x16x32_bf16 v[102:105], v[184:187], v[200:203], v[102:105]
	v_mfma_f32_16x16x32_bf16 v[94:97], v[174:177], v[208:211], v[94:97]
	v_mfma_f32_16x16x32_bf16 v[86:89], v[184:187], v[208:211], v[86:89]
	v_mfma_f32_16x16x32_bf16 v[78:81], v[174:177], v[216:219], v[78:81]
	v_mfma_f32_16x16x32_bf16 v[70:73], v[184:187], v[216:219], v[70:73]
	s_setprio 0
	s_barrier
; #define PG8_LAS __attribute__((address_space(3)))
; __device__ __forceinline__ float sum4(const f32x4 v) { return (v[0] + v[1]) + (v[2] + v[3]); }
;     __device__ __forceinline__ void operator()(const f32x4 (&acc)[2][2][4][2], const Unit& u, int wr, int wc, int fr, int fq) const {
;     ...
;         if (u.pm == pm0 || u.pm == pm1) { const PG8_LAS float* tb = (u.pm == pm0) ? rs_lds : rs_lds1;
; #pragma unroll
;             for (int ai = 0; ai < 2; ++ai)
; #pragma unroll
;                 for (int m = 0; m < 4; ++m) rsv[ai][m] = tb[ai * HALF + wr * 64 + m * 16 + fr];
;         } else {
; #pragma unroll
;             for (int ai = 0; ai < 2; ++ai)
; #pragma unroll
;                 for (int m = 0; m < 4; ++m) { const int row = row0 + ai * HALF + m * 16;
;                     const f32x4* sp = (const f32x4*)(ssq + (size_t)row * 32 + fq * 8); float s = sum4(sp[0]) + sum4(sp[1]);
	s_add_u32 s44, s44, 0x8000
	s_addc_u32 s45, s45, 0
	s_mov_b32 m0, s92
	v_lshl_add_u64 v[220:221], s[44:45], 0, v[130:131]
	ds_read_b128 v[188:191], v170 offset:49152
	ds_read_b128 v[192:195], v170 offset:50176
	ds_read_b128 v[196:199], v170 offset:51200
	ds_read_b128 v[200:203], v170 offset:52224
	ds_read_b128 v[204:207], v170 offset:53248
	ds_read_b128 v[208:211], v170 offset:54272
	ds_read_b128 v[212:215], v170 offset:55296
	ds_read_b128 v[216:219], v170 offset:56320
	global_load_lds_dwordx4 v[220:221], off
	v_lshl_add_u64 v[222:223], v[220:221], 0, s[10:11]
	s_mov_b32 m0, s93
	v_lshl_add_u64 v[220:221], v[220:221], 0, s[12:13]
	global_load_lds_dwordx4 v[222:223], off
	v_lshl_add_u64 v[222:223], s[44:45], 0, v[134:135]
	s_mov_b32 m0, s94
	s_mov_b64 s[44:45], 0x8000
	global_load_lds_dwordx4 v[222:223], off
	s_mov_b32 m0, s95
	s_nop 0
	global_load_lds_dwordx4 v[220:221], off
	v_lshl_add_u64 v[220:221], v[164:165], 0, s[44:45]
	s_mov_b32 m0, s76
	v_lshl_add_u64 v[164:165], v[164:165], 0, s[34:35]
	global_load_lds_dwordx4 v[220:221], off
	s_mov_b32 m0, s77
	s_nop 0
	global_load_lds_dwordx4 v[164:165], off
	s_waitcnt vmcnt(8)
	s_waitcnt lgkmcnt(0)
	s_barrier
	s_setprio 1
	s_waitcnt lgkmcnt(0)
	v_mfma_f32_16x16x32_bf16 v[58:61], v[144:147], v[188:191], v[58:61]
	v_mfma_f32_16x16x32_bf16 v[50:53], v[152:155], v[188:191], v[50:53]
	v_mfma_f32_16x16x32_bf16 v[42:45], v[144:147], v[196:199], v[42:45]
	v_mfma_f32_16x16x32_bf16 v[34:37], v[152:155], v[196:199], v[34:37]
	v_mfma_f32_16x16x32_bf16 v[26:29], v[144:147], v[204:207], v[26:29]
	v_mfma_f32_16x16x32_bf16 v[18:21], v[152:155], v[204:207], v[18:21]
	v_mfma_f32_16x16x32_bf16 v[10:13], v[144:147], v[212:215], v[10:13]
	v_mfma_f32_16x16x32_bf16 v[2:5], v[152:155], v[212:215], v[2:5]
	v_mfma_f32_16x16x32_bf16 v[58:61], v[148:151], v[192:195], v[58:61]
	v_mfma_f32_16x16x32_bf16 v[50:53], v[156:159], v[192:195], v[50:53]
	v_mfma_f32_16x16x32_bf16 v[42:45], v[148:151], v[200:203], v[42:45]
	v_mfma_f32_16x16x32_bf16 v[34:37], v[156:159], v[200:203], v[34:37]
	v_mfma_f32_16x16x32_bf16 v[26:29], v[148:151], v[208:211], v[26:29]
	v_mfma_f32_16x16x32_bf16 v[18:21], v[156:159], v[208:211], v[18:21]
	v_mfma_f32_16x16x32_bf16 v[10:13], v[148:151], v[216:219], v[10:13]
	v_mfma_f32_16x16x32_bf16 v[2:5], v[156:159], v[216:219], v[2:5]
	s_setprio 0
	s_setprio 1
	v_mfma_f32_16x16x32_bf16 v[66:69], v[160:163], v[188:191], v[66:69]
	v_mfma_f32_16x16x32_bf16 v[54:57], v[178:181], v[188:191], v[54:57]
	v_mfma_f32_16x16x32_bf16 v[46:49], v[160:163], v[196:199], v[46:49]
	v_mfma_f32_16x16x32_bf16 v[38:41], v[178:181], v[196:199], v[38:41]
	v_mfma_f32_16x16x32_bf16 v[30:33], v[160:163], v[204:207], v[30:33]
	v_mfma_f32_16x16x32_bf16 v[22:25], v[178:181], v[204:207], v[22:25]
	v_mfma_f32_16x16x32_bf16 v[14:17], v[160:163], v[212:215], v[14:17]
	v_mfma_f32_16x16x32_bf16 v[6:9], v[178:181], v[212:215], v[6:9]
	v_mfma_f32_16x16x32_bf16 v[66:69], v[174:177], v[192:195], v[66:69]
	v_mfma_f32_16x16x32_bf16 v[54:57], v[184:187], v[192:195], v[54:57]
	v_mfma_f32_16x16x32_bf16 v[46:49], v[174:177], v[200:203], v[46:49]
	v_mfma_f32_16x16x32_bf16 v[38:41], v[184:187], v[200:203], v[38:41]
	v_mfma_f32_16x16x32_bf16 v[30:33], v[174:177], v[208:211], v[30:33]
	v_mfma_f32_16x16x32_bf16 v[22:25], v[184:187], v[208:211], v[22:25]
	v_mfma_f32_16x16x32_bf16 v[14:17], v[174:177], v[216:219], v[14:17]
	v_mfma_f32_16x16x32_bf16 v[6:9], v[184:187], v[216:219], v[6:9]
	s_setprio 0
	s_barrier
	s_add_i32 s60, s60, 2
	s_add_u32 s6, s6, 0x10000
	s_addc_u32 s7, s7, 0
	s_add_u32 s46, s46, 0x10000
	s_addc_u32 s47, s47, 0
	s_cmp_gt_u32 s60, 29
	s_cbranch_scc0 .LBB0_799
	s_cmpk_gt_u32 s51, 0xff
	s_cbranch_scc1 .Lgu_ae0
	s_barrier
.Lgu_ae0:
	s_lshl_b32 s1, s8, 8
	s_add_i32 s1, s1, s74
	s_cmp_eq_u32 s8, s48
	s_cselect_b64 s[44:45], -1, 0
	s_cmp_eq_u32 s8, s50
	s_cselect_b64 s[6:7], -1, 0
	v_or_b32_e32 v154, s1, v1
	s_or_b64 s[8:9], s[44:45], s[6:7]
	s_mov_b64 s[6:7], -1
	s_and_b64 vcc, exec, s[8:9]
	v_or_b32_e32 v132, 16, v154
	v_or_b32_e32 v174, 32, v154
	v_or_b32_e32 v175, 48, v154
	v_add_u32_e32 v176, 0x80, v154
	v_add_u32_e32 v177, 0x90, v154
	v_add_u32_e32 v178, 0xa0, v154
	v_add_u32_e32 v179, 0xb0, v154
	s_cbranch_vccnz .LBB0_802
	v_ashrrev_i32_e32 v155, 31, v154
	v_lshlrev_b64 v[142:143], 7, v[154:155]
	v_or_b32_e32 v156, 16, v154
	v_lshl_add_u64 v[142:143], v[136:137], 0, v[142:143]
	v_ashrrev_i32_e32 v157, 31, v156
	global_load_dwordx4 v[144:147], v[142:143], off
	global_load_dwordx4 v[148:151], v[142:143], off offset:16
	v_lshlrev_b64 v[142:143], 7, v[156:157]
	v_lshl_add_u64 v[142:143], v[136:137], 0, v[142:143]
	global_load_dwordx4 v[158:161], v[142:143], off
	global_load_dwordx4 v[162:165], v[142:143], off offset:16
	v_or_b32_e32 v152, 32, v154
	v_ashrrev_i32_e32 v153, 31, v152
	v_lshlrev_b64 v[142:143], 7, v[152:153]
	v_lshl_add_u64 v[142:143], v[136:137], 0, v[142:143]
	global_load_dwordx4 v[184:187], v[142:143], off
	global_load_dwordx4 v[188:191], v[142:143], off offset:16
	v_and_b32_e32 v143, 64, v173
	v_xor_b32_e32 v153, 16, v173
	v_add_u32_e32 v157, 64, v143
	v_xor_b32_e32 v155, 32, v173
	v_cmp_lt_i32_e32 vcc, v153, v157
	v_or_b32_e32 v142, 48, v154
	v_ashrrev_i32_e32 v143, 31, v142
	v_cndmask_b32_e32 v153, v173, v153, vcc
	v_cmp_lt_i32_e32 vcc, v155, v157
	v_lshlrev_b64 v[180:181], 7, v[142:143]
	v_lshlrev_b32_e32 v153, 2, v153
	v_cndmask_b32_e32 v155, v173, v155, vcc
	v_lshlrev_b32_e32 v143, 2, v155
	v_lshl_add_u64 v[180:181], v[136:137], 0, v[180:181]
	s_waitcnt vmcnt(0)
; __device__ __forceinline__ float sum4(const f32x4 v) { return (v[0] + v[1]) + (v[2] + v[3]); }
;     __device__ __forceinline__ void operator()(const f32x4 (&acc)[2][2][4][2], const Unit& u, int wr, int wc, int fr, int fq) const {
;     ...
; #pragma unroll
;             for (int ai = 0; ai < 2; ++ai)
; #pragma unroll
;                 for (int m = 0; m < 4; ++m) { const int row = row0 + ai * HALF + m * 16;
;                     const f32x4* sp = (const f32x4*)(ssq + (size_t)row * 32 + fq * 8); float s = sum4(sp[0]) + sum4(sp[1]);
;                     s += __shfl_xor(s, 16); s += __shfl_xor(s, 32);
;                     rsv[ai][m] = 1.0f / sqrtf(s * inv_n + RMS_EPS); }
	v_mov_b32_e32 v192, v144
	v_mov_b32_e32 v193, v148
	v_mov_b32_e32 v148, v145
	v_mov_b32_e32 v144, v146
	v_mov_b32_e32 v145, v150
	v_mov_b32_e32 v150, v147
	v_pk_add_f32 v[146:147], v[192:193], v[148:149]
	v_pk_add_f32 v[144:145], v[144:145], v[150:151]
	v_mov_b32_e32 v148, v158
	v_mov_b32_e32 v149, v162
	v_mov_b32_e32 v162, v159
	v_mov_b32_e32 v150, v160
	v_mov_b32_e32 v151, v164
	v_mov_b32_e32 v164, v161
	v_pk_add_f32 v[144:145], v[146:147], v[144:145]
	v_pk_add_f32 v[146:147], v[148:149], v[162:163]
	v_pk_add_f32 v[148:149], v[150:151], v[164:165]
	v_add_f32_e32 v155, v144, v145
	v_pk_add_f32 v[144:145], v[146:147], v[148:149]
	ds_bpermute_b32 v148, v153, v155
	v_add_f32_e32 v144, v144, v145
	ds_bpermute_b32 v145, v153, v144
	v_mov_b32_e32 v158, v184
	v_mov_b32_e32 v159, v188
	v_mov_b32_e32 v188, v185
	v_mov_b32_e32 v160, v186
	v_mov_b32_e32 v161, v190
	v_mov_b32_e32 v190, v187
	v_pk_add_f32 v[150:151], v[158:159], v[188:189]
	v_pk_add_f32 v[158:159], v[160:161], v[190:191]
	s_waitcnt lgkmcnt(1)
	v_add_f32_e32 v148, v155, v148
	v_pk_add_f32 v[146:147], v[150:151], v[158:159]
	s_waitcnt lgkmcnt(0)
	v_add_f32_e32 v155, v144, v145
	v_add_f32_e32 v149, v146, v147
	global_load_dwordx4 v[144:147], v[180:181], off
	global_load_dwordx4 v[158:161], v[180:181], off offset:16
	ds_bpermute_b32 v151, v143, v148
	ds_bpermute_b32 v150, v153, v149
	ds_bpermute_b32 v157, v143, v155
	s_waitcnt lgkmcnt(2)
	v_add_f32_e32 v148, v148, v151
	v_fmamk_f32 v148, v148, 0x3a000000, v171
	s_waitcnt lgkmcnt(1)
	v_add_f32_e32 v162, v149, v150
	s_waitcnt lgkmcnt(0)
	v_add_f32_e32 v149, v155, v157
	v_mul_f32_e32 v150, 0x4f800000, v148
	v_cmp_gt_f32_e32 vcc, s83, v148
	v_fmamk_f32 v149, v149, 0x3a000000, v171
	v_cmp_gt_f32_e64 s[6:7], s83, v149
	v_cndmask_b32_e32 v148, v148, v150, vcc
	v_mul_f32_e32 v150, 0x4f800000, v149
	v_sqrt_f32_e32 v151, v148
	v_cndmask_b32_e64 v149, v149, v150, s[6:7]
	v_sqrt_f32_e32 v150, v149
	v_add_u32_e32 v155, -1, v151
	v_add_u32_e32 v157, 1, v151
	v_fma_f32 v163, -v155, v151, v148
	v_fma_f32 v164, -v157, v151, v148
	v_add_u32_e32 v165, -1, v150
	v_cmp_ge_f32_e64 s[8:9], 0, v163
	v_add_u32_e32 v180, 1, v150
	v_fma_f32 v163, -v180, v150, v149
	v_cndmask_b32_e64 v151, v151, v155, s[8:9]
	v_fma_f32 v155, -v165, v150, v149
	v_cmp_lt_f32_e64 s[8:9], 0, v164
	s_nop 1
	v_cndmask_b32_e64 v151, v151, v157, s[8:9]
	v_cmp_ge_f32_e64 s[8:9], 0, v155
	v_mul_f32_e32 v155, 0x37800000, v151
	v_cndmask_b32_e32 v151, v151, v155, vcc
	v_cndmask_b32_e64 v150, v150, v165, s[8:9]
	v_cmp_lt_f32_e64 s[8:9], 0, v163
	v_cmp_class_f32_e32 vcc, v148, v172
	s_nop 0
	v_cndmask_b32_e64 v150, v150, v180, s[8:9]
	v_mul_f32_e32 v155, 0x37800000, v150
	v_cndmask_b32_e32 v148, v151, v148, vcc
	v_cndmask_b32_e64 v150, v150, v155, s[6:7]
	v_div_scale_f32 v151, s[6:7], v148, v148, 1.0
	v_cmp_class_f32_e32 vcc, v149, v172
	s_nop 1
	v_cndmask_b32_e32 v155, v150, v149, vcc
	v_rcp_f32_e32 v149, v151
	v_div_scale_f32 v157, s[6:7], v155, v155, 1.0
	v_rcp_f32_e32 v163, v157
	v_fma_f32 v164, -v151, v149, 1.0
	v_div_scale_f32 v150, vcc, 1.0, v148, 1.0
	v_fmac_f32_e32 v149, v164, v149
	v_fma_f32 v164, -v157, v163, 1.0
	v_mul_f32_e32 v165, v150, v149
	v_fmac_f32_e32 v163, v164, v163
	v_fma_f32 v164, -v151, v165, v150
	v_fmac_f32_e32 v165, v164, v149
	v_fma_f32 v150, -v151, v165, v150
	v_div_fmas_f32 v149, v150, v149, v165
	v_add_u32_e32 v150, 0x80, v154
	v_ashrrev_i32_e32 v151, 31, v150
	v_div_fixup_f32 v164, v149, v148, 1.0
	v_lshlrev_b64 v[148:149], 7, v[150:151]
	ds_bpermute_b32 v165, v143, v162
	v_lshl_add_u64 v[148:149], v[136:137], 0, v[148:149]
	global_load_dwordx4 v[184:187], v[148:149], off
	global_load_dwordx4 v[188:191], v[148:149], off offset:16
	v_div_scale_f32 v148, vcc, 1.0, v155, 1.0
	s_waitcnt lgkmcnt(0)
	v_add_f32_e32 v149, v162, v165
	v_fmamk_f32 v149, v149, 0x3a000000, v171
	v_mul_f32_e32 v162, 0x4f800000, v149
	v_cmp_gt_f32_e64 s[6:7], s83, v149
	v_mul_f32_e32 v151, v148, v163
	v_fma_f32 v165, -v157, v151, v148
	v_cndmask_b32_e64 v149, v149, v162, s[6:7]
	v_sqrt_f32_e32 v162, v149
	v_fmac_f32_e32 v151, v165, v163
	v_fma_f32 v157, -v157, v151, v148
	v_add_u32_e32 v148, -1, v162
	v_fma_f32 v165, -v148, v162, v149
	v_cmp_ge_f32_e64 s[8:9], 0, v165
	v_add_u32_e32 v165, 1, v162
	s_nop 0
	v_cndmask_b32_e64 v148, v162, v148, s[8:9]
	v_fma_f32 v162, -v165, v162, v149
	v_cmp_lt_f32_e64 s[8:9], 0, v162
	s_nop 1
	v_cndmask_b32_e64 v148, v148, v165, s[8:9]
	v_mul_f32_e32 v162, 0x37800000, v148
	v_cndmask_b32_e64 v148, v148, v162, s[6:7]
	v_cmp_class_f32_e64 s[6:7], v149, v172
	s_nop 1
	v_cndmask_b32_e64 v162, v148, v149, s[6:7]
	s_waitcnt vmcnt(3)
	v_mov_b32_e32 v148, v144
	s_waitcnt vmcnt(2)
	v_mov_b32_e32 v149, v158
	v_mov_b32_e32 v158, v145
	v_pk_add_f32 v[144:145], v[148:149], v[158:159]
	v_mov_b32_e32 v148, v146
	v_mov_b32_e32 v149, v160
	v_mov_b32_e32 v160, v147
	v_pk_add_f32 v[146:147], v[148:149], v[160:161]
	v_div_scale_f32 v180, s[6:7], v162, v162, 1.0
	v_pk_add_f32 v[144:145], v[144:145], v[146:147]
	v_rcp_f32_e32 v181, v180
	v_add_f32_e32 v144, v144, v145
	ds_bpermute_b32 v145, v153, v144
	v_div_fmas_f32 v146, v157, v163, v151
	v_add_u32_e32 v148, 0x90, v154
	v_div_fixup_f32 v165, v146, v155, 1.0
	v_fma_f32 v146, -v180, v181, 1.0
	v_ashrrev_i32_e32 v149, 31, v148
	v_fmac_f32_e32 v181, v146, v181
	s_waitcnt lgkmcnt(0)
	v_add_f32_e32 v146, v144, v145
	v_lshlrev_b64 v[144:145], 7, v[148:149]
	v_lshl_add_u64 v[144:145], v[136:137], 0, v[144:145]
	global_load_dwordx4 v[158:161], v[144:145], off
	global_load_dwordx4 v[192:195], v[144:145], off offset:16
	ds_bpermute_b32 v147, v143, v146
	v_div_scale_f32 v144, vcc, 1.0, v162, 1.0
	v_mul_f32_e32 v149, v144, v181
	s_waitcnt lgkmcnt(0)
; __device__ __forceinline__ float sum4(const f32x4 v) { return (v[0] + v[1]) + (v[2] + v[3]); }
;     __device__ __forceinline__ void operator()(const f32x4 (&acc)[2][2][4][2], const Unit& u, int wr, int wc, int fr, int fq) const {
;     ...
; #pragma unroll
;             for (int ai = 0; ai < 2; ++ai)
; #pragma unroll
;                 for (int m = 0; m < 4; ++m) { const int row = row0 + ai * HALF + m * 16;
;                     const f32x4* sp = (const f32x4*)(ssq + (size_t)row * 32 + fq * 8); float s = sum4(sp[0]) + sum4(sp[1]);
;                     s += __shfl_xor(s, 16); s += __shfl_xor(s, 32);
;                     rsv[ai][m] = 1.0f / sqrtf(s * inv_n + RMS_EPS); }
	v_add_f32_e32 v145, v146, v147
	v_fmamk_f32 v145, v145, 0x3a000000, v171
	v_mul_f32_e32 v146, 0x4f800000, v145
	v_cmp_gt_f32_e64 s[6:7], s83, v145
	v_fma_f32 v147, -v180, v149, v144
	v_fmac_f32_e32 v149, v147, v181
	v_cndmask_b32_e64 v145, v145, v146, s[6:7]
	v_sqrt_f32_e32 v146, v145
	v_fma_f32 v151, -v180, v149, v144
	v_add_u32_e32 v144, -1, v146
	v_fma_f32 v147, -v144, v146, v145
	v_cmp_ge_f32_e64 s[8:9], 0, v147
	v_add_u32_e32 v147, 1, v146
	s_nop 0
	v_cndmask_b32_e64 v144, v146, v144, s[8:9]
	v_fma_f32 v146, -v147, v146, v145
	v_cmp_lt_f32_e64 s[8:9], 0, v146
	s_nop 1
	v_cndmask_b32_e64 v144, v144, v147, s[8:9]
	v_mul_f32_e32 v146, 0x37800000, v144
	v_cndmask_b32_e64 v144, v144, v146, s[6:7]
	v_cmp_class_f32_e64 s[6:7], v145, v172
	s_waitcnt vmcnt(3)
	v_mov_b32_e32 v146, v186
	s_waitcnt vmcnt(2)
	v_mov_b32_e32 v147, v190
	v_cndmask_b32_e64 v155, v144, v145, s[6:7]
	v_mov_b32_e32 v144, v184
	v_mov_b32_e32 v145, v188
	v_mov_b32_e32 v188, v185
	v_mov_b32_e32 v190, v187
	v_div_scale_f32 v157, s[6:7], v155, v155, 1.0
	v_pk_add_f32 v[144:145], v[144:145], v[188:189]
	v_pk_add_f32 v[146:147], v[146:147], v[190:191]
	v_rcp_f32_e32 v163, v157
	v_pk_add_f32 v[144:145], v[144:145], v[146:147]
	v_div_fmas_f32 v146, v151, v181, v149
	v_add_f32_e32 v144, v144, v145
	ds_bpermute_b32 v145, v153, v144
	v_div_fixup_f32 v162, v146, v162, 1.0
	v_fma_f32 v146, -v157, v163, 1.0
	v_fmac_f32_e32 v163, v146, v163
	v_add_u32_e32 v146, 0xa0, v154
	v_ashrrev_i32_e32 v147, 31, v146
	s_waitcnt lgkmcnt(0)
	v_add_f32_e32 v149, v144, v145
	v_lshlrev_b64 v[144:145], 7, v[146:147]
	v_lshl_add_u64 v[144:145], v[136:137], 0, v[144:145]
	ds_bpermute_b32 v151, v143, v149
	global_load_dwordx4 v[184:187], v[144:145], off
	global_load_dwordx4 v[188:191], v[144:145], off offset:16
	v_div_scale_f32 v144, vcc, 1.0, v155, 1.0
	v_mul_f32_e32 v147, v144, v163
	s_waitcnt lgkmcnt(0)
	v_add_f32_e32 v145, v149, v151
	v_fmamk_f32 v145, v145, 0x3a000000, v171
	v_mul_f32_e32 v149, 0x4f800000, v145
	v_cmp_gt_f32_e64 s[6:7], s83, v145
	v_fma_f32 v151, -v157, v147, v144
	v_fmac_f32_e32 v147, v151, v163
	v_cndmask_b32_e64 v145, v145, v149, s[6:7]
	v_sqrt_f32_e32 v149, v145
	v_fma_f32 v151, -v157, v147, v144
	v_add_u32_e32 v144, -1, v149
	v_fma_f32 v157, -v144, v149, v145
	v_cmp_ge_f32_e64 s[8:9], 0, v157
	v_add_u32_e32 v157, 1, v149
	s_nop 0
	v_cndmask_b32_e64 v144, v149, v144, s[8:9]
	v_fma_f32 v149, -v157, v149, v145
	v_cmp_lt_f32_e64 s[8:9], 0, v149
	s_nop 1
	v_cndmask_b32_e64 v144, v144, v157, s[8:9]
	v_mul_f32_e32 v149, 0x37800000, v144
	v_cndmask_b32_e64 v144, v144, v149, s[6:7]
	v_cmp_class_f32_e64 s[6:7], v145, v172
	s_nop 1
	v_cndmask_b32_e64 v149, v144, v145, s[6:7]
	s_waitcnt vmcnt(3)
	v_mov_b32_e32 v144, v158
	s_waitcnt vmcnt(2)
	v_mov_b32_e32 v145, v192
	v_mov_b32_e32 v192, v159
	v_mov_b32_e32 v158, v160
	v_mov_b32_e32 v159, v194
	v_mov_b32_e32 v194, v161
	v_pk_add_f32 v[144:145], v[144:145], v[192:193]
	v_pk_add_f32 v[158:159], v[158:159], v[194:195]
	v_div_scale_f32 v157, s[6:7], v149, v149, 1.0
	v_pk_add_f32 v[144:145], v[144:145], v[158:159]
	v_rcp_f32_e32 v180, v157
	v_add_f32_e32 v160, v144, v145
	v_add_u32_e32 v144, 0xb0, v154
	v_ashrrev_i32_e32 v145, 31, v144
	v_lshlrev_b64 v[158:159], 7, v[144:145]
	v_lshl_add_u64 v[158:159], v[136:137], 0, v[158:159]
	global_load_dwordx4 v[192:195], v[158:159], off
	global_load_dwordx4 v[196:199], v[158:159], off offset:16
	ds_bpermute_b32 v161, v153, v160
	v_div_fmas_f32 v145, v151, v163, v147
	v_div_fixup_f32 v163, v145, v155, 1.0
	v_fma_f32 v145, -v157, v180, 1.0
	v_fmac_f32_e32 v180, v145, v180
	s_waitcnt lgkmcnt(0)
	v_add_f32_e32 v147, v160, v161
	ds_bpermute_b32 v151, v143, v147
	v_div_scale_f32 v145, vcc, 1.0, v149, 1.0
	v_mul_f32_e32 v155, v145, v180
	v_fma_f32 v158, -v157, v155, v145
	s_waitcnt lgkmcnt(0)
	v_add_f32_e32 v147, v147, v151
	v_fmamk_f32 v147, v147, 0x3a000000, v171
	v_mul_f32_e32 v151, 0x4f800000, v147
	v_cmp_gt_f32_e64 s[6:7], s83, v147
	v_fmac_f32_e32 v155, v158, v180
	v_fma_f32 v145, -v157, v155, v145
	v_cndmask_b32_e64 v147, v147, v151, s[6:7]
	v_sqrt_f32_e32 v151, v147
	v_div_fmas_f32 v145, v145, v180, v155
	v_add_u32_e32 v157, -1, v151
	v_fma_f32 v158, -v157, v151, v147
	v_cmp_ge_f32_e64 s[8:9], 0, v158
	v_add_u32_e32 v158, 1, v151
	s_waitcnt vmcnt(3)
; __device__ __forceinline__ float sum4(const f32x4 v) { return (v[0] + v[1]) + (v[2] + v[3]); }
;     __device__ __forceinline__ void operator()(const f32x4 (&acc)[2][2][4][2], const Unit& u, int wr, int wc, int fr, int fq) const {
;     ...
; #pragma unroll
;             for (int ai = 0; ai < 2; ++ai)
; #pragma unroll
;                 for (int m = 0; m < 4; ++m) { const int row = row0 + ai * HALF + m * 16;
;                     const f32x4* sp = (const f32x4*)(ssq + (size_t)row * 32 + fq * 8); float s = sum4(sp[0]) + sum4(sp[1]);
;                     s += __shfl_xor(s, 16); s += __shfl_xor(s, 32);
;                     rsv[ai][m] = 1.0f / sqrtf(s * inv_n + RMS_EPS); }
	v_mov_b32_e32 v160, v186
	v_cndmask_b32_e64 v157, v151, v157, s[8:9]
	v_fma_f32 v151, -v158, v151, v147
	v_cmp_lt_f32_e64 s[8:9], 0, v151
	s_waitcnt vmcnt(2)
	v_mov_b32_e32 v159, v188
	v_mov_b32_e32 v188, v185
	v_cndmask_b32_e64 v151, v157, v158, s[8:9]
	v_mov_b32_e32 v158, v184
	v_mov_b32_e32 v161, v190
	v_mov_b32_e32 v190, v187
	v_pk_add_f32 v[158:159], v[158:159], v[188:189]
	v_pk_add_f32 v[160:161], v[160:161], v[190:191]
	v_mul_f32_e32 v157, 0x37800000, v151
	v_pk_add_f32 v[158:159], v[158:159], v[160:161]
	v_div_fixup_f32 v160, v145, v149, 1.0
	v_add_f32_e32 v158, v158, v159
	ds_bpermute_b32 v159, v153, v158
	v_cndmask_b32_e64 v151, v151, v157, s[6:7]
	v_cmp_class_f32_e64 s[6:7], v147, v172
	s_waitcnt lgkmcnt(0)
	v_add_f32_e32 v149, v158, v159
	ds_bpermute_b32 v155, v143, v149
	v_cndmask_b32_e64 v147, v151, v147, s[6:7]
	v_div_scale_f32 v151, s[6:7], v147, v147, 1.0
	v_rcp_f32_e32 v157, v151
	s_waitcnt lgkmcnt(0)
	v_add_f32_e32 v149, v149, v155
	v_fmamk_f32 v149, v149, 0x3a000000, v171
	v_mul_f32_e32 v155, 0x4f800000, v149
	v_cmp_gt_f32_e64 s[6:7], s83, v149
	v_fma_f32 v145, -v151, v157, 1.0
	v_fmac_f32_e32 v157, v145, v157
	v_cndmask_b32_e64 v149, v149, v155, s[6:7]
	v_div_scale_f32 v145, vcc, 1.0, v147, 1.0
	v_sqrt_f32_e32 v155, v149
	v_mul_f32_e32 v161, v145, v157
	v_fma_f32 v158, -v151, v161, v145
	v_fmac_f32_e32 v161, v158, v157
	v_fma_f32 v145, -v151, v161, v145
	v_add_u32_e32 v151, -1, v155
	v_fma_f32 v158, -v151, v155, v149
	v_cmp_ge_f32_e64 s[8:9], 0, v158
	v_add_u32_e32 v158, 1, v155
	v_div_fmas_f32 v145, v145, v157, v161
	v_cndmask_b32_e64 v151, v155, v151, s[8:9]
	v_fma_f32 v155, -v158, v155, v149
	v_cmp_lt_f32_e64 s[8:9], 0, v155
	s_waitcnt vmcnt(1)
	v_mov_b32_e32 v180, v194
	s_waitcnt vmcnt(0)
	v_mov_b32_e32 v159, v196
	v_cndmask_b32_e64 v151, v151, v158, s[8:9]
	v_mov_b32_e32 v158, v192
	v_mov_b32_e32 v196, v193
	v_mov_b32_e32 v181, v198
	v_mov_b32_e32 v198, v195
	v_pk_add_f32 v[158:159], v[158:159], v[196:197]
	v_pk_add_f32 v[180:181], v[180:181], v[198:199]
	v_div_fixup_f32 v161, v145, v147, 1.0
	v_pk_add_f32 v[158:159], v[158:159], v[180:181]
	v_mul_f32_e32 v155, 0x37800000, v151
	v_add_f32_e32 v158, v158, v159
	ds_bpermute_b32 v153, v153, v158
	v_cndmask_b32_e64 v151, v151, v155, s[6:7]
	v_cmp_class_f32_e64 s[6:7], v149, v172
	s_waitcnt lgkmcnt(0)
	v_add_f32_e32 v147, v158, v153
	ds_bpermute_b32 v143, v143, v147
	v_cndmask_b32_e64 v149, v151, v149, s[6:7]
	v_div_scale_f32 v151, s[6:7], v149, v149, 1.0
	v_rcp_f32_e32 v155, v151
	s_waitcnt lgkmcnt(0)
	v_add_f32_e32 v143, v147, v143
	v_fmamk_f32 v143, v143, 0x3a000000, v171
	v_mul_f32_e32 v147, 0x4f800000, v143
	v_cmp_gt_f32_e64 s[6:7], s83, v143
	v_fma_f32 v145, -v151, v155, 1.0
	v_fmac_f32_e32 v155, v145, v155
	v_cndmask_b32_e64 v143, v143, v147, s[6:7]
	v_div_scale_f32 v145, vcc, 1.0, v149, 1.0
	v_sqrt_f32_e32 v147, v143
	v_mul_f32_e32 v153, v145, v155
	v_fma_f32 v157, -v151, v153, v145
	v_fmac_f32_e32 v153, v157, v155
	v_fma_f32 v145, -v151, v153, v145
	v_add_u32_e32 v151, -1, v147
	v_fma_f32 v157, -v151, v147, v143
	v_cmp_ge_f32_e64 s[8:9], 0, v157
	v_add_u32_e32 v157, 1, v147
	v_div_fmas_f32 v145, v145, v155, v153
	v_cndmask_b32_e64 v151, v147, v151, s[8:9]
	v_fma_f32 v147, -v157, v147, v143
	v_cmp_lt_f32_e64 s[8:9], 0, v147
	v_div_fixup_f32 v158, v145, v149, 1.0
	s_nop 0
	v_cndmask_b32_e64 v147, v151, v157, s[8:9]
	v_mul_f32_e32 v151, 0x37800000, v147
	v_cndmask_b32_e64 v147, v147, v151, s[6:7]
	v_cmp_class_f32_e64 s[6:7], v143, v172
	s_nop 1
	v_cndmask_b32_e64 v143, v147, v143, s[6:7]
	v_div_scale_f32 v147, s[6:7], v143, v143, 1.0
	v_rcp_f32_e32 v151, v147
	s_mov_b64 s[6:7], 0
	v_fma_f32 v145, -v147, v151, 1.0
	v_fmac_f32_e32 v151, v145, v151
	v_div_scale_f32 v145, vcc, 1.0, v143, 1.0
	v_mul_f32_e32 v149, v145, v151
	v_fma_f32 v153, -v147, v149, v145
	v_fmac_f32_e32 v149, v153, v151
	v_fma_f32 v145, -v147, v149, v145
	v_div_fmas_f32 v145, v145, v151, v149
	v_div_fixup_f32 v159, v145, v143, 1.0
